# attention chunk loop: static s_setprio 1 for waves 4-7 (second-dispatched half), reset before the RG-LRU part
# baseline (speedup 1.0000x reference)
.LBB0_263:
	s_or_b64 exec, exec, s[0:1]
	s_and_b64 vcc, exec, s[44:45]
	s_waitcnt lgkmcnt(0)
	s_barrier
	s_cbranch_vccnz .LBB0_294
	v_readfirstlane_b32 s16, v2
	s_nop 1
	s_cmp_lt_u32 s16, 0x100
	s_cbranch_scc1 .Lattn_prio_done
	s_setprio 1
.Lattn_prio_done:
	v_ashrrev_i32_e32 v163, 6, v2
	v_mul_lo_u32 v3, v163, s75
	s_load_dword s2, s[78:79], 0x0
	v_add_u32_e32 v162, 0, v3
	ds_read_b32 v165, v162 offset:1024
	s_movk_i32 s15, 0x1bf0
	v_and_b32_e32 v3, 63, v2
	v_and_b32_e32 v164, 31, v2
	v_mad_u64_u32 v[4:5], s[16:17], v163, s15, v[162:163]
	v_and_b32_e32 v6, 0xffffffc0, v2
	v_lshrrev_b32_e32 v2, 2, v2
	s_waitcnt lgkmcnt(0)
	s_cmpk_eq_i32 s2, 0x100
	v_lshlrev_b32_e32 v5, 4, v3
	v_ashrrev_i32_e32 v7, 31, v6
	v_and_b32_e32 v2, 8, v2
	v_lshlrev_b32_e32 v8, 3, v3
	s_mov_b64 s[52:53], s[18:19]
	s_cselect_b64 s[0:1], -1, 0
	v_or_b32_e32 v166, 32, v164
	v_lshlrev_b32_e32 v168, 1, v2
	v_add_u32_e32 v167, v4, v5
	v_lshlrev_b32_e32 v170, 1, v8
	v_lshlrev_b64 v[172:173], 1, v[6:7]
	v_readlane_b32 s15, v253, 0
	s_branch .LBB0_267

.LBB0_294:
	s_setprio 0
	v_readlane_b32 s16, v254, 31
	v_readlane_b32 s17, v254, 32
	v_mov_b32 v20, v0
	s_andn2_b64 vcc, exec, s[16:17]
	v_and_b32_e32 v21, 7, v20
	v_cndmask_b32_e64 v2, 0, 1, s[16:17]
	s_waitcnt vmcnt(13)
	v_ashrrev_i32_e32 v118, 3, v20
	v_cmp_ne_u32_e64 s[0:1], 1, v2
	v_lshlrev_b32_e32 v90, 4, v21
	s_cbranch_vccnz .LBB0_304
	v_readlane_b32 s2, v254, 51
	s_add_u32 s16, s60, s2
	v_readlane_b32 s2, v254, 34
	s_addc_u32 s17, s61, 0
	v_mov_b32_e32 v91, v196
	v_add_u32_e32 v14, s2, v118
	v_mov_b32_e32 v2, v196
	v_mov_b32_e32 v3, v196
	v_lshl_add_u64 v[18:19], s[16:17], 0, v[90:91]
	v_cmp_lt_i32_e32 vcc, -1, v14
	v_mov_b64_e32 v[6:7], v[2:3]
	v_mov_b64_e32 v[8:9], v[2:3]
	s_and_saveexec_b64 s[16:17], vcc
	s_cbranch_execz .LBB0_297
	v_readlane_b32 s2, v254, 36
	s_nop 1
	v_add_u32_e32 v4, s2, v14
	s_movk_i32 s2, 0xc00
	v_mad_u64_u32 v[4:5], s[36:37], v4, s2, v[18:19]
	global_load_dwordx4 v[6:9], v[4:5], off
